# ctx units on RG workgroups 64..127 + dt pass always spread + store drain before the in-projection K-loop
# speedup vs baseline: 1.0070x; 1.0054x over previous
.LBB0_467:
	s_ashr_i32 s65, s64, 31
	s_lshl_b64 s[14:15], s[64:65], 19
	s_add_u32 s76, s19, s14
	s_addc_u32 s77, s42, s15
	s_and_b64 s[14:15], s[70:71], exec
	s_cselect_b32 s9, s77, s7
	s_cselect_b32 s13, s76, s6
	s_ashr_i32 s55, s54, 31
	s_lshl_b64 s[14:15], s[54:55], 19
	s_add_u32 s78, s43, s14
	s_addc_u32 s79, s46, s15
	s_and_b64 s[14:15], s[70:71], exec
	s_cselect_b32 s16, s79, s11
	s_cselect_b32 s17, s78, s10
	s_add_u32 s6, s6, 0x40080
	s_addc_u32 s7, s7, 0
	s_add_u32 s33, s10, 0x100
	v_mov_b32_e32 v34, 0
	s_addc_u32 s34, s11, 0
	s_mov_b32 s35, -2
	v_mov_b32_e32 v35, v34
	v_mov_b32_e32 v36, v34
	v_mov_b32_e32 v37, v34
	v_mov_b32_e32 v38, v34
	v_mov_b32_e32 v39, v34
	v_mov_b32_e32 v40, v34
	v_mov_b32_e32 v41, v34
	v_mov_b32_e32 v50, v34
	v_mov_b32_e32 v51, v34
	v_mov_b32_e32 v52, v34
	v_mov_b32_e32 v53, v34
	v_mov_b32_e32 v54, v34
	v_mov_b32_e32 v55, v34
	v_mov_b32_e32 v56, v34
	v_mov_b32_e32 v57, v34
	v_mov_b32_e32 v74, v34
	v_mov_b32_e32 v75, v34
	v_mov_b32_e32 v76, v34
	v_mov_b32_e32 v77, v34
	v_mov_b32_e32 v78, v34
	v_mov_b32_e32 v79, v34
	v_mov_b32_e32 v80, v34
	v_mov_b32_e32 v81, v34
	v_mov_b32_e32 v98, v34
	v_mov_b32_e32 v99, v34
	v_mov_b32_e32 v100, v34
	v_mov_b32_e32 v101, v34
	v_mov_b32_e32 v102, v34
	v_mov_b32_e32 v103, v34
	v_mov_b32_e32 v104, v34
	v_mov_b32_e32 v105, v34
	v_mov_b32_e32 v42, v34
	v_mov_b32_e32 v43, v34
	v_mov_b32_e32 v44, v34
	v_mov_b32_e32 v45, v34
	v_mov_b32_e32 v46, v34
	v_mov_b32_e32 v47, v34
	v_mov_b32_e32 v48, v34
	v_mov_b32_e32 v49, v34
	v_mov_b32_e32 v58, v34
	v_mov_b32_e32 v59, v34
	v_mov_b32_e32 v60, v34
	v_mov_b32_e32 v61, v34
	v_mov_b32_e32 v62, v34
	v_mov_b32_e32 v63, v34
	v_mov_b32_e32 v64, v34
	v_mov_b32_e32 v65, v34
	v_mov_b32_e32 v90, v34
	v_mov_b32_e32 v91, v34
	v_mov_b32_e32 v92, v34
	v_mov_b32_e32 v93, v34
	v_mov_b32_e32 v94, v34
	v_mov_b32_e32 v95, v34
	v_mov_b32_e32 v96, v34
	v_mov_b32_e32 v97, v34
	v_mov_b32_e32 v106, v34
	v_mov_b32_e32 v107, v34
	v_mov_b32_e32 v108, v34
	v_mov_b32_e32 v109, v34
	v_mov_b32_e32 v110, v34
	v_mov_b32_e32 v111, v34
	v_mov_b32_e32 v112, v34
	v_mov_b32_e32 v113, v34
	v_mov_b32_e32 v114, v34
	s_waitcnt vmcnt(0)
	v_mov_b32_e32 v115, v34
	v_mov_b32_e32 v116, v34
	v_mov_b32_e32 v117, v34
	v_mov_b32_e32 v118, v34
	v_mov_b32_e32 v119, v34
	v_mov_b32_e32 v120, v34
	v_mov_b32_e32 v121, v34
	v_mov_b32_e32 v130, v34
	v_mov_b32_e32 v131, v34
	v_mov_b32_e32 v132, v34
	v_mov_b32_e32 v133, v34
	v_mov_b32_e32 v134, v34
	v_mov_b32_e32 v135, v34
	v_mov_b32_e32 v136, v34
	v_mov_b32_e32 v137, v34
	v_mov_b32_e32 v146, v34
	v_mov_b32_e32 v147, v34
	v_mov_b32_e32 v148, v34
	v_mov_b32_e32 v149, v34
	v_mov_b32_e32 v150, v34
	v_mov_b32_e32 v151, v34
	v_mov_b32_e32 v152, v34
	v_mov_b32_e32 v153, v34
	v_mov_b32_e32 v162, v34
	v_mov_b32_e32 v163, v34
	v_mov_b32_e32 v164, v34
	v_mov_b32_e32 v165, v34
	v_mov_b32_e32 v166, v34
	v_mov_b32_e32 v167, v34
	v_mov_b32_e32 v168, v34
	v_mov_b32_e32 v169, v34
	v_mov_b32_e32 v122, v34
	v_mov_b32_e32 v123, v34
	v_mov_b32_e32 v124, v34
	v_mov_b32_e32 v125, v34
	v_mov_b32_e32 v126, v34
	v_mov_b32_e32 v127, v34
	v_mov_b32_e32 v128, v34
	v_mov_b32_e32 v129, v34
	v_mov_b32_e32 v138, v34
	v_mov_b32_e32 v139, v34
	v_mov_b32_e32 v140, v34
	v_mov_b32_e32 v141, v34
	v_mov_b32_e32 v142, v34
	v_mov_b32_e32 v143, v34
	v_mov_b32_e32 v144, v34
	v_mov_b32_e32 v145, v34
	v_mov_b32_e32 v154, v34
	v_mov_b32_e32 v155, v34
	v_mov_b32_e32 v156, v34
	v_mov_b32_e32 v157, v34
	v_mov_b32_e32 v158, v34
	v_mov_b32_e32 v159, v34
	v_mov_b32_e32 v160, v34
	v_mov_b32_e32 v161, v34
	v_mov_b32_e32 v170, v34
	v_mov_b32_e32 v171, v34
	v_mov_b32_e32 v172, v34
	v_mov_b32_e32 v173, v34
	v_mov_b32_e32 v174, v34
	v_mov_b32_e32 v175, v34
	v_mov_b32_e32 v176, v34
	v_mov_b32_e32 v177, v34
